# C-phase out-proj: H residual reads moved from the serialized read-modify-write epilogue into the K loop (4 chunks of 8 quads, f32 adds into accumulators), epilogue is stores only
# speedup vs baseline: 1.0003x; 1.0003x over previous
; __device__ __forceinline__ int otid() { int t = threadIdx.x; asm volatile("" : "+v"(t)); return t; }
; template <int MI, bool SWAP, bool F8 = false>
; __device__ __forceinline__ void gemm_core(const bf16_t* __restrict__ A, int lda, const bf16_t* __restrict__ B, int ldb,
;                                           int K, char* smem, f32x4 (&acc)[MI][4]) {
;   const int tid = otid(), lane = tid & 63, w = tid >> 6, wm = w >> 1, wn = w & 1;
;   const int lr = tid >> 3, lc = tid & 7;
;   const int li = lane & 15, g = lane >> 4;
;   u32x4 ra[MI], rb[4];
;   const bf16_t* ap = A + (size_t)lr * lda + lc * 8;
;   const bf16_t* bp = B + (size_t)lr * ldb + lc * 8;
; #pragma unroll
;   for (int i = 0; i < MI; ++i)
; #pragma unroll
;     for (int j = 0; j < 4; ++j) acc[i][j] = (f32x4){0.f, 0.f, 0.f, 0.f};
;   const int nk = K >> 6;
; #pragma unroll
;   for (int i = 0; i < MI; ++i) ra[i] = *(const u32x4*)(ap + (size_t)(32 * i) * lda);
; #pragma unroll
;   for (int i = 0; i < 4; ++i) rb[i] = *(const u32x4*)(bp + (size_t)(32 * i) * ldb);
;   const int woff = lr * 128 + ((lc ^ (lr & 7)) << 4);
;   const int xrow = (wm * 16 * MI + li) * 128;
;   const int wrow = 32768 + (wn * 32 + li) * 128;
; template <bool ACCUM, int MI>
; __device__ void gemm_tile_f32(const bf16_t* A, int lda, const bf16_t* B, int ldb, int K, float* C, int ldc, char* smem) {
;   f32x4 acc[MI][4];
;   gemm_core<MI, false>(A, lda, B, ldb, K, smem, acc);
.LBB0_235:
	s_lshl_b32 s10, s23, 11
	s_and_b32 s66, s10, 0x1c0000
	s_lshl_b32 s10, s25, 3
	s_and_b32 s10, s10, 56
	s_ashr_i32 s30, s25, 6
	s_add_i32 s20, s10, s30
	s_ashr_i32 s21, s20, 31
	v_mov_b32_e32 v30, v208
	s_and_b32 s27, s24, 56
	s_lshl_b64 s[10:11], s[20:21], 18
	s_lshl_b64 s[20:21], s[20:21], 19
	s_add_u32 s20, s6, s20
	v_ashrrev_i32_e32 v2, 3, v30
	v_ashrrev_i32_e32 v3, 31, v2
	s_addc_u32 s21, s7, s21
	v_lshlrev_b64 v[20:21], 11, v[2:3]
	v_lshlrev_b32_e32 v0, 4, v30
	v_lshl_add_u64 v[24:25], s[20:21], 0, v[20:21]
	v_and_b32_e32 v0, 0x70, v0
	v_lshl_add_u64 v[24:25], v[24:25], 0, v[0:1]
	v_add_co_u32_e32 v26, vcc, s93, v24
	s_lshl_b32 s26, s25, 4
	s_nop 0
	v_addc_co_u32_e32 v27, vcc, 0, v25, vcc
	v_lshrrev_b32_e32 v254, 3, v208
	v_and_b32_e32 v254, 7, v254
	v_xor_b32_e32 v252, v254, v208
	v_and_b32_e32 v252, 7, v252
	v_lshlrev_b32_e32 v252, 4, v252
	v_lshl_or_b32 v252, v254, 11, v252
	v_add_u32_e32 v253, 0x10000, v252
	v_lshrrev_b32_e32 v254, 6, v208
	s_nop 0
	v_readfirstlane_b32 s62, v254
	s_lshl_b32 s62, s62, 10
	v_readfirstlane_b32 s56, v24
	v_readfirstlane_b32 s57, v25
	v_add_co_u32_e32 v26, vcc, s46, v24
	s_and_b32 s26, s26, 0x380
	s_nop 0
	v_addc_co_u32_e32 v27, vcc, 0, v25, vcc
	v_add_co_u32_e32 v28, vcc, s47, v24
	s_lshl_b32 s28, s26, 11
	s_nop 0
	v_addc_co_u32_e32 v29, vcc, 0, v25, vcc
	v_add_co_u32_e32 v26, vcc, s50, v24
	s_mov_b32 s20, 0x60000
	s_nop 0
	v_addc_co_u32_e32 v27, vcc, 0, v25, vcc
	v_add_co_u32_e32 v28, vcc, s51, v24
	s_add_u32 s28, s19, s28
	s_nop 0
	v_addc_co_u32_e32 v29, vcc, 0, v25, vcc
	v_add_co_u32_e32 v26, vcc, s20, v24
	s_addc_u32 s29, s22, 0
	s_nop 0
	v_addc_co_u32_e32 v27, vcc, 0, v25, vcc
	s_mov_b32 s20, 0x70000
	v_lshl_add_u64 v[22:23], s[28:29], 0, v[20:21]
	v_add_co_u32_e32 v24, vcc, s20, v24
	v_lshl_add_u64 v[22:23], v[22:23], 0, v[0:1]
	s_nop 0
	v_addc_co_u32_e32 v25, vcc, 0, v25, vcc
	v_add_co_u32_e32 v24, vcc, s93, v22
	v_lshlrev_b32_e32 v0, 7, v2
	s_nop 0
	v_addc_co_u32_e32 v25, vcc, 0, v23, vcc
	s_nop 0
	v_readfirstlane_b32 s58, v22
	v_readfirstlane_b32 s59, v23
	v_add_co_u32_e32 v24, vcc, s46, v22
	v_xor_b32_e32 v2, v2, v30
	s_nop 0
	v_addc_co_u32_e32 v25, vcc, 0, v23, vcc
	v_add_co_u32_e32 v22, vcc, s47, v22
	v_lshlrev_b32_e32 v2, 4, v2
	s_nop 0
	v_addc_co_u32_e32 v23, vcc, 0, v23, vcc
	v_and_or_b32 v0, v2, s33, v0
	v_lshlrev_b32_e32 v2, 7, v30
	v_and_b32_e32 v3, 15, v30
	v_and_b32_e32 v202, 0xffffc780, v2
	v_lshrrev_b32_e32 v2, 1, v30
	v_lshrrev_b32_e32 v31, 4, v30
	v_and_or_b32 v2, v2, 32, v3
	v_and_b32_e32 v23, 7, v30
	s_add_i32 s20, s30, s27
	v_bfe_u32 v22, v30, 4, 2
	v_lshlrev_b32_e32 v203, 7, v2
	v_bitop3_b32 v2, v31, v23, 3 bitop3:0x6c
	s_ashr_i32 s21, s20, 31
	v_lshlrev_b32_e32 v204, 4, v2
	v_bitop3_b32 v2, v22, v23, 4 bitop3:0x36
	s_lshl_b64 s[20:21], s[20:21], 19
	v_lshlrev_b32_e32 v205, 4, v2
	v_lshl_add_u64 v[2:3], s[20:21], 0, v[20:21]
	v_lshlrev_b32_e32 v22, 4, v23
	v_lshl_add_u64 v[20:21], s[66:67], 0, v[20:21]
	v_or_b32_e32 v2, v2, v22
	v_or_b32_e32 v20, v20, v22
	v_mov_b32_e32 v144, 0
	v_lshl_add_u64 v[2:3], s[12:13], 0, v[2:3]
	v_lshl_add_u64 v[200:201], s[8:9], 0, v[20:21]
	s_mov_b64 s[20:21], 0
	v_mov_b32_e32 v145, v144
	v_mov_b32_e32 v146, v144
	v_mov_b32_e32 v147, v144
	v_mov_b32_e32 v100, v144
	v_mov_b32_e32 v101, v144
	v_mov_b32_e32 v102, v144
	v_mov_b32_e32 v103, v144
	v_mov_b32_e32 v112, v144
	v_mov_b32_e32 v113, v144
	v_mov_b32_e32 v114, v144
	v_mov_b32_e32 v115, v144
	v_mov_b32_e32 v116, v144
	v_mov_b32_e32 v117, v144
	v_mov_b32_e32 v118, v144
	v_mov_b32_e32 v119, v144
	v_mov_b32_e32 v120, v144
	v_mov_b32_e32 v121, v144
	v_mov_b32_e32 v122, v144
	v_mov_b32_e32 v123, v144
	v_mov_b32_e32 v128, v144
	v_mov_b32_e32 v129, v144
	v_mov_b32_e32 v130, v144
	v_mov_b32_e32 v131, v144
	v_mov_b32_e32 v76, v144
	v_mov_b32_e32 v77, v144
	v_mov_b32_e32 v78, v144
	v_mov_b32_e32 v79, v144
	v_mov_b32_e32 v72, v144
	v_mov_b32_e32 v73, v144
	v_mov_b32_e32 v74, v144
	v_mov_b32_e32 v75, v144
	v_mov_b32_e32 v64, v144
	v_mov_b32_e32 v65, v144
	v_mov_b32_e32 v66, v144
	v_mov_b32_e32 v67, v144
	v_mov_b32_e32 v68, v144
	v_mov_b32_e32 v69, v144
	v_mov_b32_e32 v70, v144
	v_mov_b32_e32 v71, v144
	v_mov_b32_e32 v20, v144
	v_mov_b32_e32 v21, v144
	v_mov_b32_e32 v22, v144
	v_mov_b32_e32 v23, v144
	v_mov_b32_e32 v24, v144
	v_mov_b32_e32 v25, v144
	v_mov_b32_e32 v26, v144
	v_mov_b32_e32 v27, v144
	v_mov_b32_e32 v28, v144
	v_mov_b32_e32 v29, v144
	v_mov_b32_e32 v30, v144
	v_mov_b32_e32 v31, v144
	v_mov_b32_e32 v32, v144
	v_mov_b32_e32 v33, v144
	v_mov_b32_e32 v34, v144
	v_mov_b32_e32 v35, v144
	v_mov_b32_e32 v36, v144
	v_mov_b32_e32 v37, v144
	v_mov_b32_e32 v38, v144
	v_mov_b32_e32 v39, v144
	v_mov_b32_e32 v40, v144
	v_mov_b32_e32 v41, v144
	v_mov_b32_e32 v42, v144
	v_mov_b32_e32 v43, v144
	v_mov_b32_e32 v44, v144
	v_mov_b32_e32 v45, v144
	v_mov_b32_e32 v46, v144
	v_mov_b32_e32 v47, v144
	v_mov_b32_e32 v48, v144
	v_mov_b32_e32 v49, v144
	v_mov_b32_e32 v50, v144
	v_mov_b32_e32 v51, v144
	v_mov_b32_e32 v52, v144
	v_mov_b32_e32 v53, v144
	v_mov_b32_e32 v54, v144
	v_mov_b32_e32 v55, v144
	v_mov_b32_e32 v56, v144
	v_mov_b32_e32 v57, v144
	v_mov_b32_e32 v58, v144
	v_mov_b32_e32 v59, v144
	v_mov_b32_e32 v60, v144
	v_mov_b32_e32 v61, v144
	v_mov_b32_e32 v62, v144
	v_mov_b32_e32 v63, v144
	v_mov_b32_e32 v80, v144
	v_mov_b32_e32 v81, v144
	v_mov_b32_e32 v82, v144
	v_mov_b32_e32 v83, v144
	v_mov_b32_e32 v84, v144
	v_mov_b32_e32 v85, v144
	v_mov_b32_e32 v86, v144
	v_mov_b32_e32 v87, v144
	v_mov_b32_e32 v88, v144
	v_mov_b32_e32 v89, v144
	v_mov_b32_e32 v90, v144
	v_mov_b32_e32 v91, v144
	v_mov_b32_e32 v92, v144
	v_mov_b32_e32 v93, v144
	v_mov_b32_e32 v94, v144
	v_mov_b32_e32 v95, v144
	v_mov_b32_e32 v96, v144
	v_mov_b32_e32 v97, v144
	v_mov_b32_e32 v98, v144
	v_mov_b32_e32 v99, v144
	v_mov_b32_e32 v104, v144
	v_mov_b32_e32 v105, v144
	v_mov_b32_e32 v106, v144
	v_mov_b32_e32 v107, v144
	v_mov_b32_e32 v108, v144
	v_mov_b32_e32 v109, v144
	v_mov_b32_e32 v110, v144
	v_mov_b32_e32 v111, v144
	v_mov_b32_e32 v124, v144
	v_mov_b32_e32 v125, v144
	v_mov_b32_e32 v126, v144
	v_mov_b32_e32 v127, v144
	v_mov_b32_e32 v132, v144
	v_mov_b32_e32 v133, v144
	v_mov_b32_e32 v134, v144
	v_mov_b32_e32 v135, v144
	v_mov_b32_e32 v136, v144
	v_mov_b32_e32 v137, v144
	v_mov_b32_e32 v138, v144
	v_mov_b32_e32 v139, v144
	v_mov_b32_e32 v140, v144
	v_mov_b32_e32 v141, v144
	v_mov_b32_e32 v142, v144
	v_mov_b32_e32 v143, v144
	s_lshl_b64 s[98:99], s[10:11], 2
	s_add_u32 s98, s16, s98
	s_addc_u32 s99, s17, s99
	s_lshl_b32 s63, s26, 2
	s_add_u32 s98, s98, s63
	s_addc_u32 s99, s99, 0
	s_mov_b32 s63, 0
	v_and_b32_e32 v236, 0x8f, v208
	v_lshrrev_b32_e32 v237, 1, v208
	v_lshlrev_b32_e32 v236, 12, v236
	v_and_b32_e32 v237, 32, v237
	v_lshrrev_b32_e32 v254, 2, v208
	s_nop 0
	v_and_or_b32 v237, v254, 12, v237
	s_nop 0
	v_lshl_add_u32 v236, v237, 2, v236
	s_nop 0
	v_mov_b32_e32 v237, v236
; template <int MI, bool SWAP, bool F8 = false>
; __device__ __forceinline__ void gemm_core(const bf16_t* __restrict__ A, int lda, const bf16_t* __restrict__ B, int ldb,
;                                           int K, char* smem, f32x4 (&acc)[MI][4]) {
;     ...
;   for (int kt = 0; kt < nk; ++kt) {
;     __syncthreads();
; #pragma unroll
;     for (int i = 0; i < MI; ++i) *(u32x4*)(smem + woff + i * 4096) = ra[i];
; #pragma unroll
;     for (int i = 0; i < 4; ++i) *(u32x4*)(smem + 32768 + woff + i * 4096) = rb[i];
;     __syncthreads();
;     if (kt + 1 < nk) {
; #pragma unroll
;       for (int i = 0; i < MI; ++i) ra[i] = *(const u32x4*)(ap + (size_t)(32 * i) * lda + (kt + 1) * 64);
; #pragma unroll
;       for (int i = 0; i < 4; ++i) rb[i] = *(const u32x4*)(bp + (size_t)(32 * i) * ldb + (kt + 1) * 64);
;     }
; template <bool ACCUM, int MI>
; __device__ void gemm_tile_f32(const bf16_t* A, int lda, const bf16_t* B, int ldb, int K, float* C, int ldc, char* smem) {
;     ...
;       f32x4* cp = (f32x4*)(C + (size_t)MROW(i) * ldc + NCOL(j));
;       f32x4 v = acc[i][j];
;       if (ACCUM) v += *cp;
;       *cp = v;
.LBB0_236:
	v_add_u32_e32 v215, v203, v204
	s_barrier
	s_mov_b32 m0, s62
	s_nop 0
	global_load_lds_dwordx4 v252, s[56:57]
	s_add_u32 m0, s62, 0x1000
	s_nop 0
	global_load_lds_dwordx4 v253, s[56:57]
	s_add_u32 s56, s56, 0x20000
	s_addc_u32 s57, s57, 0
	s_add_u32 m0, s62, 0x2000
	s_nop 0
	global_load_lds_dwordx4 v252, s[56:57]
	s_add_u32 m0, s62, 0x3000
	s_nop 0
	global_load_lds_dwordx4 v253, s[56:57]
	s_add_u32 s56, s56, 0x20000
	s_addc_u32 s57, s57, 0
	s_add_u32 m0, s62, 0x4000
	s_nop 0
	global_load_lds_dwordx4 v252, s[56:57]
	s_add_u32 m0, s62, 0x5000
	s_nop 0
	global_load_lds_dwordx4 v253, s[56:57]
	s_add_u32 s56, s56, 0x20000
	s_addc_u32 s57, s57, 0
	s_add_u32 m0, s62, 0x6000
	s_nop 0
	global_load_lds_dwordx4 v252, s[56:57]
	s_add_u32 m0, s62, 0x7000
	s_nop 0
	global_load_lds_dwordx4 v253, s[56:57]
	s_sub_u32 s56, s56, 0x60000
	s_subb_u32 s57, s57, 0
	s_add_u32 m0, s62, 0x8000
	s_nop 0
	global_load_lds_dwordx4 v252, s[58:59]
	s_add_u32 m0, s62, 0x9000
	s_nop 0
	global_load_lds_dwordx4 v253, s[58:59]
	s_add_u32 s58, s58, 0x20000
	s_addc_u32 s59, s59, 0
	s_add_u32 m0, s62, 0xa000
	s_nop 0
	global_load_lds_dwordx4 v252, s[58:59]
	s_add_u32 m0, s62, 0xb000
	s_nop 0
	global_load_lds_dwordx4 v253, s[58:59]
	s_sub_u32 s58, s58, 0x20000
	s_subb_u32 s59, s59, 0
	v_add_u32_e32 v252, 0x80, v252
	v_add_u32_e32 v253, 0x80, v253
	s_waitcnt vmcnt(0)
	s_cmp_gt_u32 s63, 12
	s_cbranch_scc1 .Lcch236_ret
	s_cmp_eq_u32 s63, 0
	s_cbranch_scc1 .Lcch236_h0
	s_cmp_eq_u32 s63, 3
	s_cbranch_scc1 .Lcch236_h1
	s_cmp_eq_u32 s63, 6
	s_cbranch_scc1 .Lcch236_h2
	s_cmp_eq_u32 s63, 9
	s_cbranch_scc1 .Lcch236_h3
	s_cmp_eq_u32 s63, 12
	s_cbranch_scc1 .Lcch236_h4
	s_branch .Lcch236_ret
.Lcch236_h0:
	global_load_dwordx4 v[4:7], v236, s[98:99]
	global_load_dwordx4 v[8:11], v236, s[98:99] offset:64
	global_load_dwordx4 v[12:15], v236, s[98:99] offset:256
	global_load_dwordx4 v[16:19], v236, s[98:99] offset:320
	v_add_u32_e32 v236, 0x10000, v236
	global_load_dwordx4 v[232:235], v236, s[98:99]
	global_load_dwordx4 v[176:179], v236, s[98:99] offset:64
	global_load_dwordx4 v[184:187], v236, s[98:99] offset:256
	global_load_dwordx4 v[188:191], v236, s[98:99] offset:320
	v_add_u32_e32 v236, 0x10000, v236
	s_branch .Lcch236_ret
.Lcch236_h1:
	v_pk_add_f32 v[140:141], v[140:141], v[4:5]
	v_pk_add_f32 v[142:143], v[142:143], v[6:7]
	v_pk_add_f32 v[136:137], v[136:137], v[8:9]
	v_pk_add_f32 v[138:139], v[138:139], v[10:11]
	v_pk_add_f32 v[132:133], v[132:133], v[12:13]
	v_pk_add_f32 v[134:135], v[134:135], v[14:15]
	v_pk_add_f32 v[124:125], v[124:125], v[16:17]
	v_pk_add_f32 v[126:127], v[126:127], v[18:19]
	v_pk_add_f32 v[108:109], v[108:109], v[232:233]
	v_pk_add_f32 v[110:111], v[110:111], v[234:235]
	v_pk_add_f32 v[104:105], v[104:105], v[176:177]
	v_pk_add_f32 v[106:107], v[106:107], v[178:179]
	v_pk_add_f32 v[96:97], v[96:97], v[184:185]
	v_pk_add_f32 v[98:99], v[98:99], v[186:187]
	v_pk_add_f32 v[92:93], v[92:93], v[188:189]
	v_pk_add_f32 v[94:95], v[94:95], v[190:191]
	global_load_dwordx4 v[4:7], v236, s[98:99]
	global_load_dwordx4 v[8:11], v236, s[98:99] offset:64
	global_load_dwordx4 v[12:15], v236, s[98:99] offset:256
	global_load_dwordx4 v[16:19], v236, s[98:99] offset:320
	v_add_u32_e32 v236, 0x10000, v236
	global_load_dwordx4 v[232:235], v236, s[98:99]
	global_load_dwordx4 v[176:179], v236, s[98:99] offset:64
	global_load_dwordx4 v[184:187], v236, s[98:99] offset:256
	global_load_dwordx4 v[188:191], v236, s[98:99] offset:320
	v_add_u32_e32 v236, 0x10000, v236
	s_branch .Lcch236_ret
.Lcch236_h2:
	v_pk_add_f32 v[88:89], v[88:89], v[4:5]
	v_pk_add_f32 v[90:91], v[90:91], v[6:7]
	v_pk_add_f32 v[84:85], v[84:85], v[8:9]
	v_pk_add_f32 v[86:87], v[86:87], v[10:11]
	v_pk_add_f32 v[80:81], v[80:81], v[12:13]
	v_pk_add_f32 v[82:83], v[82:83], v[14:15]
	v_pk_add_f32 v[60:61], v[60:61], v[16:17]
	v_pk_add_f32 v[62:63], v[62:63], v[18:19]
	v_pk_add_f32 v[56:57], v[56:57], v[232:233]
	v_pk_add_f32 v[58:59], v[58:59], v[234:235]
	v_pk_add_f32 v[52:53], v[52:53], v[176:177]
	v_pk_add_f32 v[54:55], v[54:55], v[178:179]
	v_pk_add_f32 v[48:49], v[48:49], v[184:185]
	v_pk_add_f32 v[50:51], v[50:51], v[186:187]
	v_pk_add_f32 v[44:45], v[44:45], v[188:189]
	v_pk_add_f32 v[46:47], v[46:47], v[190:191]
	global_load_dwordx4 v[4:7], v236, s[98:99]
	global_load_dwordx4 v[8:11], v236, s[98:99] offset:64
	global_load_dwordx4 v[12:15], v236, s[98:99] offset:256
	global_load_dwordx4 v[16:19], v236, s[98:99] offset:320
	v_add_u32_e32 v236, 0x10000, v236
	global_load_dwordx4 v[232:235], v236, s[98:99]
	global_load_dwordx4 v[176:179], v236, s[98:99] offset:64
	global_load_dwordx4 v[184:187], v236, s[98:99] offset:256
	global_load_dwordx4 v[188:191], v236, s[98:99] offset:320
	v_add_u32_e32 v236, 0x10000, v236
	s_branch .Lcch236_ret
.Lcch236_h3:
	v_pk_add_f32 v[40:41], v[40:41], v[4:5]
	v_pk_add_f32 v[42:43], v[42:43], v[6:7]
	v_pk_add_f32 v[36:37], v[36:37], v[8:9]
	v_pk_add_f32 v[38:39], v[38:39], v[10:11]
	v_pk_add_f32 v[32:33], v[32:33], v[12:13]
	v_pk_add_f32 v[34:35], v[34:35], v[14:15]
	v_pk_add_f32 v[28:29], v[28:29], v[16:17]
	v_pk_add_f32 v[30:31], v[30:31], v[18:19]
	v_pk_add_f32 v[24:25], v[24:25], v[232:233]
	v_pk_add_f32 v[26:27], v[26:27], v[234:235]
	v_pk_add_f32 v[20:21], v[20:21], v[176:177]
	v_pk_add_f32 v[22:23], v[22:23], v[178:179]
	v_pk_add_f32 v[68:69], v[68:69], v[184:185]
	v_pk_add_f32 v[70:71], v[70:71], v[186:187]
	v_pk_add_f32 v[64:65], v[64:65], v[188:189]
	v_pk_add_f32 v[66:67], v[66:67], v[190:191]
	global_load_dwordx4 v[4:7], v236, s[98:99]
	global_load_dwordx4 v[8:11], v236, s[98:99] offset:64
	global_load_dwordx4 v[12:15], v236, s[98:99] offset:256
	global_load_dwordx4 v[16:19], v236, s[98:99] offset:320
	v_add_u32_e32 v236, 0x10000, v236
	global_load_dwordx4 v[232:235], v236, s[98:99]
	global_load_dwordx4 v[176:179], v236, s[98:99] offset:64
	global_load_dwordx4 v[184:187], v236, s[98:99] offset:256
	global_load_dwordx4 v[188:191], v236, s[98:99] offset:320
	v_add_u32_e32 v236, 0x10000, v236
	s_branch .Lcch236_ret
; template <int MI, bool SWAP, bool F8 = false>
; __device__ __forceinline__ void gemm_core(const bf16_t* __restrict__ A, int lda, const bf16_t* __restrict__ B, int ldb,
;                                           int K, char* smem, f32x4 (&acc)[MI][4]) {
;     ...
;     for (int kk = 0; kk < 2; ++kk) {
;       const int ch = ((kk * 4 + g) ^ (li & 7)) << 4;
;       bf16x8 xf[MI], wf[4];
; #pragma unroll
;       for (int j = 0; j < 4; ++j) wf[j] = *(const bf16x8*)(smem + wrow + ((j & 1) * 16 + (j >> 1) * 64) * 128 + ch);
; #pragma unroll
;       for (int i = 0; i < MI; ++i) xf[i] = *(const bf16x8*)(smem + xrow + i * 2048 + ch);
; #pragma unroll
;       for (int i = 0; i < MI; ++i)
; #pragma unroll
;         for (int j = 0; j < 4; ++j) {
;           if (SWAP) acc[i][j] = __builtin_amdgcn_mfma_f32_16x16x32_bf16(xf[i], wf[j], acc[i][j], 0, 0, 0);
;           else acc[i][j] = __builtin_amdgcn_mfma_f32_16x16x32_bf16(wf[j], xf[i], acc[i][j], 0, 0, 0);
;         }
;     }
; template <bool ACCUM, int MI>
; __device__ void gemm_tile_f32(const bf16_t* A, int lda, const bf16_t* B, int ldb, int K, float* C, int ldc, char* smem) {
;     ...
;       if (ACCUM) v += *cp;
.Lcch236_h4:
	v_pk_add_f32 v[72:73], v[72:73], v[4:5]
	v_pk_add_f32 v[74:75], v[74:75], v[6:7]
	v_pk_add_f32 v[76:77], v[76:77], v[8:9]
	v_pk_add_f32 v[78:79], v[78:79], v[10:11]
	v_pk_add_f32 v[128:129], v[128:129], v[12:13]
	v_pk_add_f32 v[130:131], v[130:131], v[14:15]
	v_pk_add_f32 v[120:121], v[120:121], v[16:17]
	v_pk_add_f32 v[122:123], v[122:123], v[18:19]
	v_pk_add_f32 v[116:117], v[116:117], v[232:233]
	v_pk_add_f32 v[118:119], v[118:119], v[234:235]
	v_pk_add_f32 v[112:113], v[112:113], v[176:177]
	v_pk_add_f32 v[114:115], v[114:115], v[178:179]
	v_pk_add_f32 v[100:101], v[100:101], v[184:185]
	v_pk_add_f32 v[102:103], v[102:103], v[186:187]
	v_pk_add_f32 v[144:145], v[144:145], v[188:189]
	v_pk_add_f32 v[146:147], v[146:147], v[190:191]
.Lcch236_ret:
	s_add_u32 s63, s63, 1
	s_barrier
	v_add_u32_e32 v213, v202, v204
	ds_read_b128 v[148:151], v215 offset:32768
	ds_read_b128 v[152:155], v215 offset:34816
	ds_read_b128 v[156:159], v213
	ds_read_b128 v[160:163], v213 offset:2048
	ds_read_b128 v[164:167], v215 offset:40960
	ds_read_b128 v[168:171], v215 offset:43008
	s_waitcnt lgkmcnt(3)
	v_mfma_f32_16x16x32_bf16 v[140:143], v[148:151], v[156:159], v[140:143]
	v_add_u32_e32 v207, v203, v205
	v_add_u32_e32 v206, v202, v205
	v_mfma_f32_16x16x32_bf16 v[136:139], v[152:155], v[156:159], v[136:139]
	s_waitcnt lgkmcnt(1)
	v_mfma_f32_16x16x32_bf16 v[132:135], v[164:167], v[156:159], v[132:135]
	s_waitcnt lgkmcnt(0)
	v_mfma_f32_16x16x32_bf16 v[124:127], v[168:171], v[156:159], v[124:127]
	v_mfma_f32_16x16x32_bf16 v[108:111], v[148:151], v[160:163], v[108:111]
	v_mfma_f32_16x16x32_bf16 v[104:107], v[152:155], v[160:163], v[104:107]
	v_mfma_f32_16x16x32_bf16 v[96:99], v[164:167], v[160:163], v[96:99]
	v_mfma_f32_16x16x32_bf16 v[92:95], v[168:171], v[160:163], v[92:95]
	ds_read_b128 v[156:159], v213 offset:4096
	ds_read_b128 v[160:163], v213 offset:6144
	s_waitcnt lgkmcnt(1)
	v_mfma_f32_16x16x32_bf16 v[88:91], v[148:151], v[156:159], v[88:91]
	v_mfma_f32_16x16x32_bf16 v[84:87], v[152:155], v[156:159], v[84:87]
	v_mfma_f32_16x16x32_bf16 v[80:83], v[164:167], v[156:159], v[80:83]
	v_mfma_f32_16x16x32_bf16 v[60:63], v[168:171], v[156:159], v[60:63]
	s_waitcnt lgkmcnt(0)
	v_mfma_f32_16x16x32_bf16 v[56:59], v[148:151], v[160:163], v[56:59]
	v_mfma_f32_16x16x32_bf16 v[52:55], v[152:155], v[160:163], v[52:55]
	v_mfma_f32_16x16x32_bf16 v[48:51], v[164:167], v[160:163], v[48:51]
	v_mfma_f32_16x16x32_bf16 v[44:47], v[168:171], v[160:163], v[44:47]
	ds_read_b128 v[156:159], v213 offset:8192
	ds_read_b128 v[160:163], v213 offset:10240
	s_waitcnt lgkmcnt(1)
	v_mfma_f32_16x16x32_bf16 v[40:43], v[148:151], v[156:159], v[40:43]
	v_mfma_f32_16x16x32_bf16 v[36:39], v[152:155], v[156:159], v[36:39]
	v_mfma_f32_16x16x32_bf16 v[32:35], v[164:167], v[156:159], v[32:35]
	v_mfma_f32_16x16x32_bf16 v[28:31], v[168:171], v[156:159], v[28:31]
	s_waitcnt lgkmcnt(0)
	v_mfma_f32_16x16x32_bf16 v[24:27], v[148:151], v[160:163], v[24:27]
	v_mfma_f32_16x16x32_bf16 v[20:23], v[152:155], v[160:163], v[20:23]
	v_mfma_f32_16x16x32_bf16 v[68:71], v[164:167], v[160:163], v[68:71]
	v_mfma_f32_16x16x32_bf16 v[64:67], v[168:171], v[160:163], v[64:67]
	ds_read_b128 v[156:159], v213 offset:12288
	ds_read_b128 v[160:163], v213 offset:14336
	ds_read_b128 v[172:175], v207 offset:32768
	ds_read_b128 v[180:183], v207 offset:34816
	s_waitcnt lgkmcnt(3)
	v_mfma_f32_16x16x32_bf16 v[72:75], v[148:151], v[156:159], v[72:75]
	v_mfma_f32_16x16x32_bf16 v[76:79], v[152:155], v[156:159], v[76:79]
	v_mfma_f32_16x16x32_bf16 v[128:131], v[164:167], v[156:159], v[128:131]
	v_mfma_f32_16x16x32_bf16 v[120:123], v[168:171], v[156:159], v[120:123]
	s_waitcnt lgkmcnt(2)
	v_mfma_f32_16x16x32_bf16 v[116:119], v[148:151], v[160:163], v[116:119]
	v_mfma_f32_16x16x32_bf16 v[112:115], v[152:155], v[160:163], v[112:115]
	ds_read_b128 v[148:151], v206
	ds_read_b128 v[152:155], v206 offset:2048
	ds_read_b128 v[192:195], v207 offset:40960
	ds_read_b128 v[196:199], v207 offset:43008
	v_mfma_f32_16x16x32_bf16 v[100:103], v[164:167], v[160:163], v[100:103]
	v_mfma_f32_16x16x32_bf16 v[144:147], v[168:171], v[160:163], v[144:147]
	s_waitcnt lgkmcnt(3)
	v_mfma_f32_16x16x32_bf16 v[140:143], v[172:175], v[148:151], v[140:143]
	v_mfma_f32_16x16x32_bf16 v[136:139], v[180:183], v[148:151], v[136:139]
	s_waitcnt lgkmcnt(1)
	v_mfma_f32_16x16x32_bf16 v[132:135], v[192:195], v[148:151], v[132:135]
	s_waitcnt lgkmcnt(0)
	v_mfma_f32_16x16x32_bf16 v[124:127], v[196:199], v[148:151], v[124:127]
	v_mfma_f32_16x16x32_bf16 v[108:111], v[172:175], v[152:155], v[108:111]
	v_mfma_f32_16x16x32_bf16 v[104:107], v[180:183], v[152:155], v[104:107]
	v_mfma_f32_16x16x32_bf16 v[96:99], v[192:195], v[152:155], v[96:99]
	v_mfma_f32_16x16x32_bf16 v[92:95], v[196:199], v[152:155], v[92:95]
	ds_read_b128 v[148:151], v206 offset:4096
	ds_read_b128 v[152:155], v206 offset:6144
	s_waitcnt lgkmcnt(1)
	v_mfma_f32_16x16x32_bf16 v[88:91], v[172:175], v[148:151], v[88:91]
	ds_read_b128 v[156:159], v206 offset:12288
	ds_read_b128 v[216:219], v206 offset:14336
	v_mfma_f32_16x16x32_bf16 v[84:87], v[180:183], v[148:151], v[84:87]
	v_mfma_f32_16x16x32_bf16 v[80:83], v[192:195], v[148:151], v[80:83]
	v_mfma_f32_16x16x32_bf16 v[60:63], v[196:199], v[148:151], v[60:63]
	ds_read_b128 v[148:151], v206 offset:8192
	s_waitcnt lgkmcnt(3)
	v_mfma_f32_16x16x32_bf16 v[56:59], v[172:175], v[152:155], v[56:59]
	v_mfma_f32_16x16x32_bf16 v[52:55], v[180:183], v[152:155], v[52:55]
	v_mfma_f32_16x16x32_bf16 v[48:51], v[192:195], v[152:155], v[48:51]
	v_mfma_f32_16x16x32_bf16 v[44:47], v[196:199], v[152:155], v[44:47]
	ds_read_b128 v[152:155], v206 offset:10240
	s_waitcnt lgkmcnt(1)
	v_mfma_f32_16x16x32_bf16 v[40:43], v[172:175], v[148:151], v[40:43]
	v_mfma_f32_16x16x32_bf16 v[36:39], v[180:183], v[148:151], v[36:39]
	v_mfma_f32_16x16x32_bf16 v[32:35], v[192:195], v[148:151], v[32:35]
	v_mfma_f32_16x16x32_bf16 v[28:31], v[196:199], v[148:151], v[28:31]
	s_waitcnt lgkmcnt(0)
	v_mfma_f32_16x16x32_bf16 v[24:27], v[172:175], v[152:155], v[24:27]
	v_mfma_f32_16x16x32_bf16 v[20:23], v[180:183], v[152:155], v[20:23]
	v_mfma_f32_16x16x32_bf16 v[68:71], v[192:195], v[152:155], v[68:71]
	v_mfma_f32_16x16x32_bf16 v[64:67], v[196:199], v[152:155], v[64:67]
	v_mfma_f32_16x16x32_bf16 v[72:75], v[172:175], v[156:159], v[72:75]
	v_mfma_f32_16x16x32_bf16 v[76:79], v[180:183], v[156:159], v[76:79]
	v_mfma_f32_16x16x32_bf16 v[128:131], v[192:195], v[156:159], v[128:131]
	v_mfma_f32_16x16x32_bf16 v[120:123], v[196:199], v[156:159], v[120:123]
	v_mfma_f32_16x16x32_bf16 v[116:119], v[172:175], v[216:219], v[116:119]
	v_mfma_f32_16x16x32_bf16 v[112:115], v[180:183], v[216:219], v[112:115]
	v_mfma_f32_16x16x32_bf16 v[100:103], v[192:195], v[216:219], v[100:103]
	v_mfma_f32_16x16x32_bf16 v[144:147], v[196:199], v[216:219], v[144:147]
	s_add_u32 s20, s20, 0x80
	s_addc_u32 s21, s21, 0
	s_cmpk_lg_i32 s20, 0x780
	s_cbranch_scc1 .LBB0_236
; template <int MI, bool SWAP, bool F8 = false>
; __device__ __forceinline__ void gemm_core(const bf16_t* __restrict__ A, int lda, const bf16_t* __restrict__ B, int ldb,
;                                           int K, char* smem, f32x4 (&acc)[MI][4]) {
;     ...
;   for (int kt = 0; kt < nk; ++kt) {
;     __syncthreads();
; #pragma unroll
;     for (int i = 0; i < MI; ++i) *(u32x4*)(smem + woff + i * 4096) = ra[i];
; #pragma unroll
;     for (int i = 0; i < 4; ++i) *(u32x4*)(smem + 32768 + woff + i * 4096) = rb[i];
;     __syncthreads();
;     if (kt + 1 < nk) {
; #pragma unroll
;       for (int i = 0; i < MI; ++i) ra[i] = *(const u32x4*)(ap + (size_t)(32 * i) * lda + (kt + 1) * 64);
; #pragma unroll
;       for (int i = 0; i < 4; ++i) rb[i] = *(const u32x4*)(bp + (size_t)(32 * i) * ldb + (kt + 1) * 64);
;     }
;     if (F8) {
;       const int c0 = (g ^ (li & 7)) << 4, c1 = ((4 + g) ^ (li & 7)) << 4;
;       i32x8 wf8[4];
; #pragma unroll
;       for (int j = 0; j < 4; ++j) {
;         const char* rp = smem + wrow + ((j & 1) * 16 + (j >> 1) * 64) * 128;
;         const u32x4 lo = *(const u32x4*)(rp + c0), hi = *(const u32x4*)(rp + c1);
;         wf8[j] = (i32x8){(int)lo.x, (int)lo.y, (int)lo.z, (int)lo.w, (int)hi.x, (int)hi.y, (int)hi.z, (int)hi.w};
;       }
; #pragma unroll
;       for (int i = 0; i < MI; ++i) {
;         const char* rp = smem + xrow + i * 2048;
;         const u32x4 lo = *(const u32x4*)(rp + c0), hi = *(const u32x4*)(rp + c1);
;         const i32x8 xf8 = {(int)lo.x, (int)lo.y, (int)lo.z, (int)lo.w, (int)hi.x, (int)hi.y, (int)hi.z, (int)hi.w};
; #pragma unroll
;         for (int j = 0; j < 4; ++j)
;           acc[i][j] = __builtin_amdgcn_mfma_scale_f32_16x16x128_f8f6f4(wf8[j], xf8, acc[i][j], 0, 0, 0, 0x77777777, 0, 0x7f7f7f7f);
;       }
;     } else {
; #pragma unroll
;     for (int kk = 0; kk < 2; ++kk) {
;       const int ch = ((kk * 4 + g) ^ (li & 7)) << 4;
;       bf16x8 xf[MI], wf[4];
; #pragma unroll
;       for (int j = 0; j < 4; ++j) wf[j] = *(const bf16x8*)(smem + wrow + ((j & 1) * 16 + (j >> 1) * 64) * 128 + ch);
; #pragma unroll
;       for (int i = 0; i < MI; ++i) xf[i] = *(const bf16x8*)(smem + xrow + i * 2048 + ch);
; #pragma unroll
;       for (int i = 0; i < MI; ++i)
; #pragma unroll
;         for (int j = 0; j < 4; ++j) {
	s_barrier
	s_mov_b32 m0, s62
	s_nop 0
	global_load_lds_dwordx4 v252, s[56:57]
	s_add_u32 m0, s62, 0x1000
	s_nop 0
	global_load_lds_dwordx4 v253, s[56:57]
	s_add_u32 s56, s56, 0x20000
	s_addc_u32 s57, s57, 0
	s_add_u32 m0, s62, 0x2000
	s_nop 0
	global_load_lds_dwordx4 v252, s[56:57]
	s_add_u32 m0, s62, 0x3000
	s_nop 0
	global_load_lds_dwordx4 v253, s[56:57]
	s_add_u32 s56, s56, 0x20000
	s_addc_u32 s57, s57, 0
	s_add_u32 m0, s62, 0x4000
	s_nop 0
	global_load_lds_dwordx4 v252, s[56:57]
	s_add_u32 m0, s62, 0x5000
	s_nop 0
	global_load_lds_dwordx4 v253, s[56:57]
	s_add_u32 s56, s56, 0x20000
	s_addc_u32 s57, s57, 0
	s_add_u32 m0, s62, 0x6000
	s_nop 0
	global_load_lds_dwordx4 v252, s[56:57]
	s_add_u32 m0, s62, 0x7000
	s_nop 0
	global_load_lds_dwordx4 v253, s[56:57]
	s_sub_u32 s56, s56, 0x60000
	s_subb_u32 s57, s57, 0
	s_add_u32 m0, s62, 0x8000
	s_nop 0
	global_load_lds_dwordx4 v252, s[58:59]
	s_add_u32 m0, s62, 0x9000
	s_nop 0
	global_load_lds_dwordx4 v253, s[58:59]
	s_add_u32 s58, s58, 0x20000
	s_addc_u32 s59, s59, 0
	s_add_u32 m0, s62, 0xa000
	s_nop 0
	global_load_lds_dwordx4 v252, s[58:59]
	s_add_u32 m0, s62, 0xb000
	s_nop 0
	global_load_lds_dwordx4 v253, s[58:59]
	s_sub_u32 s58, s58, 0x20000
	s_subb_u32 s59, s59, 0
	s_waitcnt vmcnt(0)
	s_barrier
	ds_read_b128 v[148:151], v215 offset:32768
	ds_read_b128 v[152:155], v215 offset:34816
	ds_read_b128 v[156:159], v215 offset:40960
	ds_read_b128 v[160:163], v215 offset:43008
	ds_read_b128 v[164:167], v213
	ds_read_b128 v[168:171], v213 offset:2048
	ds_read_b128 v[172:175], v213 offset:4096
	ds_read_b128 v[176:179], v213 offset:6144
	ds_read_b128 v[180:183], v213 offset:8192
	ds_read_b128 v[184:187], v213 offset:10240
	ds_read_b128 v[188:191], v213 offset:12288
	ds_read_b128 v[192:195], v213 offset:14336
	s_waitcnt lgkmcnt(7)
	v_mfma_f32_16x16x32_bf16 v[132:135], v[156:159], v[164:167], v[132:135]
	s_lshl_b64 s[10:11], s[10:11], 2
	s_add_u32 s10, s16, s10
	s_addc_u32 s11, s17, s11
	v_mfma_f32_16x16x32_bf16 v[140:143], v[148:151], v[164:167], v[140:143]
	s_lshl_b32 s20, s26, 2
	s_add_u32 s10, s10, s20
	s_addc_u32 s11, s11, 0
	v_mfma_f32_16x16x32_bf16 v[136:139], v[152:155], v[164:167], v[136:139]
	s_add_i32 s25, s25, s78
	s_add_i32 s24, s24, s71
	s_add_i32 s23, s23, s76
	v_mfma_f32_16x16x32_bf16 v[124:127], v[160:163], v[164:167], v[124:127]
	s_cmpk_gt_i32 s25, 0x1ff
	s_waitcnt lgkmcnt(6)
	v_mfma_f32_16x16x32_bf16 v[108:111], v[148:151], v[168:171], v[108:111]
	v_mfma_f32_16x16x32_bf16 v[104:107], v[152:155], v[168:171], v[104:107]
	v_mfma_f32_16x16x32_bf16 v[96:99], v[156:159], v[168:171], v[96:99]
	v_mfma_f32_16x16x32_bf16 v[92:95], v[160:163], v[168:171], v[92:95]
	s_waitcnt lgkmcnt(5)
	v_mfma_f32_16x16x32_bf16 v[88:91], v[148:151], v[172:175], v[88:91]
	v_mfma_f32_16x16x32_bf16 v[84:87], v[152:155], v[172:175], v[84:87]
	v_mfma_f32_16x16x32_bf16 v[80:83], v[156:159], v[172:175], v[80:83]
	v_mfma_f32_16x16x32_bf16 v[60:63], v[160:163], v[172:175], v[60:63]
	s_waitcnt lgkmcnt(4)
	v_mfma_f32_16x16x32_bf16 v[56:59], v[148:151], v[176:179], v[56:59]
	v_mfma_f32_16x16x32_bf16 v[52:55], v[152:155], v[176:179], v[52:55]
	v_mfma_f32_16x16x32_bf16 v[48:51], v[156:159], v[176:179], v[48:51]
	v_mfma_f32_16x16x32_bf16 v[44:47], v[160:163], v[176:179], v[44:47]
	s_waitcnt lgkmcnt(3)
	v_mfma_f32_16x16x32_bf16 v[40:43], v[148:151], v[180:183], v[40:43]
	v_mfma_f32_16x16x32_bf16 v[36:39], v[152:155], v[180:183], v[36:39]
	v_mfma_f32_16x16x32_bf16 v[32:35], v[156:159], v[180:183], v[32:35]
	v_mfma_f32_16x16x32_bf16 v[28:31], v[160:163], v[180:183], v[28:31]
	s_waitcnt lgkmcnt(2)
	v_mfma_f32_16x16x32_bf16 v[24:27], v[148:151], v[184:187], v[24:27]
	v_mfma_f32_16x16x32_bf16 v[20:23], v[152:155], v[184:187], v[20:23]
	v_mfma_f32_16x16x32_bf16 v[164:167], v[156:159], v[184:187], v[68:71]
	v_mfma_f32_16x16x32_bf16 v[168:171], v[160:163], v[184:187], v[64:67]
	s_waitcnt lgkmcnt(1)
	v_mfma_f32_16x16x32_bf16 v[172:175], v[148:151], v[188:191], v[72:75]
	v_mfma_f32_16x16x32_bf16 v[176:179], v[152:155], v[188:191], v[76:79]
	v_mfma_f32_16x16x32_bf16 v[180:183], v[156:159], v[188:191], v[128:131]
	v_mfma_f32_16x16x32_bf16 v[184:187], v[160:163], v[188:191], v[120:123]
	s_waitcnt lgkmcnt(0)
	v_mfma_f32_16x16x32_bf16 v[148:151], v[148:151], v[192:195], v[116:119]
	v_mfma_f32_16x16x32_bf16 v[152:155], v[152:155], v[192:195], v[112:115]
	v_mfma_f32_16x16x32_bf16 v[156:159], v[156:159], v[192:195], v[100:103]
	v_mfma_f32_16x16x32_bf16 v[144:147], v[160:163], v[192:195], v[144:147]
	ds_read_b128 v[160:163], v207 offset:32768
	ds_read_b128 v[188:191], v207 offset:34816
	ds_read_b128 v[192:195], v207 offset:40960
	ds_read_b128 v[196:199], v207 offset:43008
	ds_read_b128 v[64:67], v206
	ds_read_b128 v[68:71], v206 offset:2048
	ds_read_b128 v[72:75], v206 offset:4096
	ds_read_b128 v[76:79], v206 offset:6144
	ds_read_b128 v[200:203], v206 offset:8192
	ds_read_b128 v[216:219], v206 offset:10240
	ds_read_b128 v[220:223], v206 offset:12288
	ds_read_b128 v[204:207], v206 offset:14336
	s_waitcnt lgkmcnt(7)
; template <bool ACCUM, int MI>
; __device__ void gemm_tile_f32(const bf16_t* A, int lda, const bf16_t* B, int ldb, int K, float* C, int ldc, char* smem) {
;     ...
; #pragma unroll
;   for (int i = 0; i < MI; ++i)
; #pragma unroll
;     for (int j = 0; j < 4; ++j) {
;       f32x4* cp = (f32x4*)(C + (size_t)MROW(i) * ldc + NCOL(j));
;       f32x4 v = acc[i][j];
;       if (ACCUM) v += *cp;
;       *cp = v;
;     }
	v_mfma_f32_16x16x32_bf16 v[224:227], v[192:195], v[64:67], v[132:135]
	v_mfma_f32_16x16x32_bf16 v[228:231], v[196:199], v[64:67], v[124:127]
	s_waitcnt lgkmcnt(6)
	v_mfma_f32_16x16x32_bf16 v[128:131], v[160:163], v[68:71], v[108:111]
	v_mfma_f32_16x16x32_bf16 v[124:127], v[188:191], v[68:71], v[104:107]
	s_waitcnt lgkmcnt(5)
	v_mfma_f32_16x16x32_bf16 v[112:115], v[160:163], v[72:75], v[88:91]
	v_mfma_f32_16x16x32_bf16 v[108:111], v[188:191], v[72:75], v[84:87]
	v_mfma_f32_16x16x32_bf16 v[104:107], v[192:195], v[72:75], v[80:83]
	v_mfma_f32_16x16x32_bf16 v[100:103], v[196:199], v[72:75], v[60:63]
	s_waitcnt lgkmcnt(3)
	v_mfma_f32_16x16x32_bf16 v[72:75], v[192:195], v[200:203], v[32:35]
	s_waitcnt lgkmcnt(0)
	v_mfma_f32_16x16x32_bf16 v[32:35], v[160:163], v[204:207], v[148:151]
	v_mfma_f32_16x16x32_bf16 v[60:63], v[188:191], v[216:219], v[20:23]
	v_mfma_f32_16x16x32_bf16 v[20:23], v[196:199], v[204:207], v[144:147]
	v_mfma_f32_16x16x32_bf16 v[140:143], v[160:163], v[64:67], v[140:143]
	v_mfma_f32_16x16x32_bf16 v[136:139], v[188:191], v[64:67], v[136:139]
	v_mfma_f32_16x16x32_bf16 v[120:123], v[192:195], v[68:71], v[96:99]
	v_mfma_f32_16x16x32_bf16 v[116:119], v[196:199], v[68:71], v[92:95]
	v_mfma_f32_16x16x32_bf16 v[96:99], v[160:163], v[76:79], v[56:59]
	v_mfma_f32_16x16x32_bf16 v[92:95], v[188:191], v[76:79], v[52:55]
	v_mfma_f32_16x16x32_bf16 v[88:91], v[192:195], v[76:79], v[48:51]
	v_mfma_f32_16x16x32_bf16 v[84:87], v[196:199], v[76:79], v[44:47]
	v_mfma_f32_16x16x32_bf16 v[80:83], v[160:163], v[200:203], v[40:43]
	v_mfma_f32_16x16x32_bf16 v[76:79], v[188:191], v[200:203], v[36:39]
	v_mfma_f32_16x16x32_bf16 v[68:71], v[196:199], v[200:203], v[28:31]
	v_mfma_f32_16x16x32_bf16 v[64:67], v[160:163], v[216:219], v[24:27]
	v_mfma_f32_16x16x32_bf16 v[56:59], v[192:195], v[216:219], v[164:167]
	v_mfma_f32_16x16x32_bf16 v[52:55], v[196:199], v[216:219], v[168:171]
	v_mfma_f32_16x16x32_bf16 v[48:51], v[160:163], v[220:223], v[172:175]
	v_mfma_f32_16x16x32_bf16 v[44:47], v[188:191], v[220:223], v[176:179]
	v_mfma_f32_16x16x32_bf16 v[40:43], v[192:195], v[220:223], v[180:183]
	v_mfma_f32_16x16x32_bf16 v[36:39], v[196:199], v[220:223], v[184:187]
	v_mfma_f32_16x16x32_bf16 v[28:31], v[188:191], v[204:207], v[152:155]
	v_mfma_f32_16x16x32_bf16 v[24:27], v[192:195], v[204:207], v[156:159]
	s_nop 7
	s_nop 7
	s_nop 7
	global_store_dwordx4 v237, v[140:143], s[98:99]
	global_store_dwordx4 v237, v[136:139], s[98:99] offset:64
	global_store_dwordx4 v237, v[224:227], s[98:99] offset:256
	global_store_dwordx4 v237, v[228:231], s[98:99] offset:320
	v_add_u32_e32 v237, 0x10000, v237
	global_store_dwordx4 v237, v[128:131], s[98:99]
	global_store_dwordx4 v237, v[124:127], s[98:99] offset:64
	global_store_dwordx4 v237, v[120:123], s[98:99] offset:256
	global_store_dwordx4 v237, v[116:119], s[98:99] offset:320
	v_add_u32_e32 v237, 0x10000, v237
	global_store_dwordx4 v237, v[112:115], s[98:99]
	global_store_dwordx4 v237, v[108:111], s[98:99] offset:64
	global_store_dwordx4 v237, v[104:107], s[98:99] offset:256
	global_store_dwordx4 v237, v[100:103], s[98:99] offset:320
	v_add_u32_e32 v237, 0x10000, v237
	global_store_dwordx4 v237, v[96:99], s[98:99]
	global_store_dwordx4 v237, v[92:95], s[98:99] offset:64
	global_store_dwordx4 v237, v[88:91], s[98:99] offset:256
	global_store_dwordx4 v237, v[84:87], s[98:99] offset:320
	v_add_u32_e32 v237, 0x10000, v237
	global_store_dwordx4 v237, v[80:83], s[98:99]
	global_store_dwordx4 v237, v[76:79], s[98:99] offset:64
	global_store_dwordx4 v237, v[72:75], s[98:99] offset:256
	global_store_dwordx4 v237, v[68:71], s[98:99] offset:320
	v_add_u32_e32 v237, 0x10000, v237
	global_store_dwordx4 v237, v[64:67], s[98:99]
	global_store_dwordx4 v237, v[60:63], s[98:99] offset:64
	global_store_dwordx4 v237, v[56:59], s[98:99] offset:256
	global_store_dwordx4 v237, v[52:55], s[98:99] offset:320
	v_add_u32_e32 v237, 0x10000, v237
	global_store_dwordx4 v237, v[48:51], s[98:99]
	global_store_dwordx4 v237, v[44:47], s[98:99] offset:64
	global_store_dwordx4 v237, v[40:43], s[98:99] offset:256
	global_store_dwordx4 v237, v[36:39], s[98:99] offset:320
	v_add_u32_e32 v237, 0x10000, v237
	global_store_dwordx4 v237, v[32:35], s[98:99]
	global_store_dwordx4 v237, v[28:31], s[98:99] offset:64
	global_store_dwordx4 v237, v[24:27], s[98:99] offset:256
	global_store_dwordx4 v237, v[20:23], s[98:99] offset:320
	s_cbranch_scc0 .LBB0_235

; __device__ __forceinline__ int otid() { int t = threadIdx.x; asm volatile("" : "+v"(t)); return t; }
; template <int MI, bool SWAP, bool F8 = false>
; __device__ __forceinline__ void gemm_core(const bf16_t* __restrict__ A, int lda, const bf16_t* __restrict__ B, int ldb,
;                                           int K, char* smem, f32x4 (&acc)[MI][4]) {
;   const int tid = otid(), lane = tid & 63, w = tid >> 6, wm = w >> 1, wn = w & 1;
;   const int lr = tid >> 3, lc = tid & 7;
;   const int li = lane & 15, g = lane >> 4;
;   u32x4 ra[MI], rb[4];
;   const bf16_t* ap = A + (size_t)lr * lda + lc * 8;
;   const bf16_t* bp = B + (size_t)lr * ldb + lc * 8;
; #pragma unroll
;   for (int i = 0; i < MI; ++i)
; #pragma unroll
;     for (int j = 0; j < 4; ++j) acc[i][j] = (f32x4){0.f, 0.f, 0.f, 0.f};
;   const int nk = K >> 6;
; #pragma unroll
;   for (int i = 0; i < MI; ++i) ra[i] = *(const u32x4*)(ap + (size_t)(32 * i) * lda);
; #pragma unroll
;   for (int i = 0; i < 4; ++i) rb[i] = *(const u32x4*)(bp + (size_t)(32 * i) * ldb);
;   const int woff = lr * 128 + ((lc ^ (lr & 7)) << 4);
;   const int xrow = (wm * 16 * MI + li) * 128;
;   const int wrow = 32768 + (wn * 32 + li) * 128;
; template <bool ACCUM, int MI>
; __device__ void gemm_tile_f32(const bf16_t* A, int lda, const bf16_t* B, int ldb, int K, float* C, int ldc, char* smem) {
;     ...
;       f32x4* cp = (f32x4*)(C + (size_t)MROW(i) * ldc + NCOL(j));
.LBB0_818:
	s_lshl_b32 s0, s19, 10
	s_and_b32 s0, s0, 0xe0000
	s_add_i32 s66, s8, s0
	s_lshl_b32 s0, s21, 3
	s_and_b32 s0, s0, 56
	s_ashr_i32 s29, s21, 6
	s_add_i32 s22, s0, s29
	s_ashr_i32 s23, s22, 31
	s_waitcnt vmcnt(17)
	v_mov_b32_e32 v30, v208
	s_and_b32 s28, s20, 56
	s_lshl_b64 s[6:7], s[66:67], 1
	s_lshl_b64 s[0:1], s[22:23], 18
	s_lshl_b64 s[22:23], s[22:23], 19
	s_add_u32 s24, s9, s22
	v_ashrrev_i32_e32 v2, 3, v30
	v_ashrrev_i32_e32 v3, 31, v2
	s_addc_u32 s25, s10, s23
	v_lshlrev_b64 v[20:21], 11, v[2:3]
	v_lshlrev_b32_e32 v0, 4, v30
	v_lshl_add_u64 v[24:25], s[24:25], 0, v[20:21]
	v_and_b32_e32 v0, 0x70, v0
	v_lshl_add_u64 v[24:25], v[24:25], 0, v[0:1]
	v_add_co_u32_e32 v26, vcc, s93, v24
	s_lshl_b32 s22, s21, 4
	s_nop 0
	v_addc_co_u32_e32 v27, vcc, 0, v25, vcc
	v_lshrrev_b32_e32 v254, 3, v208
	v_and_b32_e32 v254, 7, v254
	v_xor_b32_e32 v252, v254, v208
	v_and_b32_e32 v252, 7, v252
	v_lshlrev_b32_e32 v252, 4, v252
	v_lshl_or_b32 v252, v254, 11, v252
	v_add_u32_e32 v253, 0x10000, v252
	v_lshrrev_b32_e32 v254, 6, v208
	s_nop 0
	v_readfirstlane_b32 s62, v254
	s_lshl_b32 s62, s62, 10
	v_readfirstlane_b32 s56, v24
	v_readfirstlane_b32 s57, v25
	v_add_co_u32_e32 v26, vcc, s46, v24
	s_and_b32 s22, s22, 0x380
	s_nop 0
	v_addc_co_u32_e32 v27, vcc, 0, v25, vcc
	v_add_co_u32_e32 v28, vcc, s47, v24
	s_lshl_b32 s23, s8, 1
	s_nop 0
	v_addc_co_u32_e32 v29, vcc, 0, v25, vcc
	v_add_co_u32_e32 v26, vcc, s50, v24
	s_lshl_b32 s26, s22, 11
	s_nop 0
	v_addc_co_u32_e32 v27, vcc, 0, v25, vcc
	s_or_b32 s23, s26, s23
	v_add_co_u32_e32 v28, vcc, s51, v24
	s_add_u32 s26, s11, s23
	s_nop 0
	v_addc_co_u32_e32 v29, vcc, 0, v25, vcc
	s_mov_b32 s23, 0x60000
	v_add_co_u32_e32 v26, vcc, s23, v24
	s_addc_u32 s27, s18, 0
	s_nop 0
	v_addc_co_u32_e32 v27, vcc, 0, v25, vcc
	s_mov_b32 s23, 0x70000
	v_lshl_add_u64 v[22:23], s[26:27], 0, v[20:21]
	v_add_co_u32_e32 v24, vcc, s23, v24
	v_lshl_add_u64 v[22:23], v[22:23], 0, v[0:1]
	s_nop 0
	v_addc_co_u32_e32 v25, vcc, 0, v25, vcc
	v_add_co_u32_e32 v24, vcc, s93, v22
	v_lshlrev_b32_e32 v0, 7, v2
	s_nop 0
	v_addc_co_u32_e32 v25, vcc, 0, v23, vcc
	s_nop 0
	v_readfirstlane_b32 s58, v22
	v_readfirstlane_b32 s59, v23
	v_add_co_u32_e32 v24, vcc, s46, v22
	v_xor_b32_e32 v2, v2, v30
	s_nop 0
	v_addc_co_u32_e32 v25, vcc, 0, v23, vcc
	v_add_co_u32_e32 v22, vcc, s47, v22
	v_lshlrev_b32_e32 v2, 4, v2
	s_nop 0
	v_addc_co_u32_e32 v23, vcc, 0, v23, vcc
	v_and_or_b32 v0, v2, s33, v0
	v_lshlrev_b32_e32 v2, 7, v30
	v_and_b32_e32 v3, 15, v30
	v_and_b32_e32 v202, 0xffffc780, v2
	v_lshrrev_b32_e32 v2, 1, v30
	v_lshrrev_b32_e32 v31, 4, v30
	v_and_or_b32 v2, v2, 32, v3
	v_and_b32_e32 v23, 7, v30
	s_add_i32 s24, s29, s28
	v_bfe_u32 v22, v30, 4, 2
	v_lshlrev_b32_e32 v203, 7, v2
	v_bitop3_b32 v2, v31, v23, 3 bitop3:0x6c
	s_ashr_i32 s25, s24, 31
	v_lshlrev_b32_e32 v204, 4, v2
	v_bitop3_b32 v2, v22, v23, 4 bitop3:0x36
	s_lshl_b64 s[24:25], s[24:25], 19
	v_lshlrev_b32_e32 v205, 4, v2
	v_lshl_add_u64 v[2:3], s[24:25], 0, v[20:21]
	v_lshlrev_b32_e32 v22, 4, v23
	s_add_u32 s6, s12, s6
	v_or_b32_e32 v2, v2, v22
	v_or_b32_e32 v20, v20, v22
	s_addc_u32 s7, s13, s7
	v_mov_b32_e32 v144, 0
	v_lshl_add_u64 v[2:3], s[12:13], 0, v[2:3]
	v_lshl_add_u64 v[200:201], s[6:7], 0, v[20:21]
	s_mov_b64 s[6:7], 0
	v_mov_b32_e32 v145, v144
	v_mov_b32_e32 v146, v144
	v_mov_b32_e32 v147, v144
	s_waitcnt vmcnt(24)
	v_mov_b32_e32 v100, v144
	v_mov_b32_e32 v101, v144
	v_mov_b32_e32 v102, v144
	v_mov_b32_e32 v103, v144
	v_mov_b32_e32 v112, v144
	v_mov_b32_e32 v113, v144
	v_mov_b32_e32 v114, v144
	v_mov_b32_e32 v115, v144
	s_waitcnt vmcnt(23)
	v_mov_b32_e32 v116, v144
	v_mov_b32_e32 v117, v144
	v_mov_b32_e32 v118, v144
	v_mov_b32_e32 v119, v144
	s_waitcnt vmcnt(22)
	v_mov_b32_e32 v120, v144
	v_mov_b32_e32 v121, v144
	v_mov_b32_e32 v122, v144
	v_mov_b32_e32 v123, v144
	s_waitcnt vmcnt(20)
	v_mov_b32_e32 v128, v144
	v_mov_b32_e32 v129, v144
	v_mov_b32_e32 v130, v144
	v_mov_b32_e32 v131, v144
	v_mov_b32_e32 v76, v144
	v_mov_b32_e32 v77, v144
	v_mov_b32_e32 v78, v144
	v_mov_b32_e32 v79, v144
	v_mov_b32_e32 v72, v144
	v_mov_b32_e32 v73, v144
	v_mov_b32_e32 v74, v144
	v_mov_b32_e32 v75, v144
	v_mov_b32_e32 v64, v144
	v_mov_b32_e32 v65, v144
	v_mov_b32_e32 v66, v144
	v_mov_b32_e32 v67, v144
	v_mov_b32_e32 v68, v144
	v_mov_b32_e32 v69, v144
	v_mov_b32_e32 v70, v144
	v_mov_b32_e32 v71, v144
	v_mov_b32_e32 v20, v144
	v_mov_b32_e32 v21, v144
	v_mov_b32_e32 v22, v144
	v_mov_b32_e32 v23, v144
	v_mov_b32_e32 v24, v144
	v_mov_b32_e32 v25, v144
	v_mov_b32_e32 v26, v144
	v_mov_b32_e32 v27, v144
	v_mov_b32_e32 v28, v144
	v_mov_b32_e32 v29, v144
	v_mov_b32_e32 v30, v144
	v_mov_b32_e32 v31, v144
	v_mov_b32_e32 v32, v144
	v_mov_b32_e32 v33, v144
	v_mov_b32_e32 v34, v144
	v_mov_b32_e32 v35, v144
	v_mov_b32_e32 v36, v144
	v_mov_b32_e32 v37, v144
	v_mov_b32_e32 v38, v144
	v_mov_b32_e32 v39, v144
	v_mov_b32_e32 v40, v144
	v_mov_b32_e32 v41, v144
	v_mov_b32_e32 v42, v144
	v_mov_b32_e32 v43, v144
	v_mov_b32_e32 v44, v144
	v_mov_b32_e32 v45, v144
	v_mov_b32_e32 v46, v144
	v_mov_b32_e32 v47, v144
	v_mov_b32_e32 v48, v144
	v_mov_b32_e32 v49, v144
	v_mov_b32_e32 v50, v144
	v_mov_b32_e32 v51, v144
	v_mov_b32_e32 v52, v144
	v_mov_b32_e32 v53, v144
	v_mov_b32_e32 v54, v144
	v_mov_b32_e32 v55, v144
	v_mov_b32_e32 v56, v144
	v_mov_b32_e32 v57, v144
	v_mov_b32_e32 v58, v144
	v_mov_b32_e32 v59, v144
	v_mov_b32_e32 v60, v144
	v_mov_b32_e32 v61, v144
	v_mov_b32_e32 v62, v144
	v_mov_b32_e32 v63, v144
	v_mov_b32_e32 v80, v144
	v_mov_b32_e32 v81, v144
	v_mov_b32_e32 v82, v144
	v_mov_b32_e32 v83, v144
	v_mov_b32_e32 v84, v144
	v_mov_b32_e32 v85, v144
	v_mov_b32_e32 v86, v144
	v_mov_b32_e32 v87, v144
	v_mov_b32_e32 v88, v144
	v_mov_b32_e32 v89, v144
	v_mov_b32_e32 v90, v144
	v_mov_b32_e32 v91, v144
	v_mov_b32_e32 v92, v144
	v_mov_b32_e32 v93, v144
	v_mov_b32_e32 v94, v144
	v_mov_b32_e32 v95, v144
	v_mov_b32_e32 v96, v144
	v_mov_b32_e32 v97, v144
	v_mov_b32_e32 v98, v144
	v_mov_b32_e32 v99, v144
	v_mov_b32_e32 v104, v144
	v_mov_b32_e32 v105, v144
	v_mov_b32_e32 v106, v144
	v_mov_b32_e32 v107, v144
	v_mov_b32_e32 v108, v144
	v_mov_b32_e32 v109, v144
	v_mov_b32_e32 v110, v144
	v_mov_b32_e32 v111, v144
	v_mov_b32_e32 v124, v144
	v_mov_b32_e32 v125, v144
	v_mov_b32_e32 v126, v144
	v_mov_b32_e32 v127, v144
	v_mov_b32_e32 v132, v144
	v_mov_b32_e32 v133, v144
	v_mov_b32_e32 v134, v144
	v_mov_b32_e32 v135, v144
	v_mov_b32_e32 v136, v144
	v_mov_b32_e32 v137, v144
	v_mov_b32_e32 v138, v144
	v_mov_b32_e32 v139, v144
	v_mov_b32_e32 v140, v144
	v_mov_b32_e32 v141, v144
	v_mov_b32_e32 v142, v144
	v_mov_b32_e32 v143, v144
	s_lshl_b64 s[98:99], s[0:1], 2
	s_add_u32 s98, s16, s98
	s_addc_u32 s99, s17, s99
	s_lshl_b32 s63, s22, 2
	s_add_u32 s98, s98, s63
	s_addc_u32 s99, s99, 0
	s_mov_b32 s63, 0
	v_and_b32_e32 v236, 0x8f, v208
	v_lshrrev_b32_e32 v237, 1, v208
	v_lshlrev_b32_e32 v236, 12, v236
	v_and_b32_e32 v237, 32, v237
	v_lshrrev_b32_e32 v254, 2, v208
	s_nop 0
	v_and_or_b32 v237, v254, 12, v237
	s_nop 0
	v_lshl_add_u32 v236, v237, 2, v236
	s_nop 0
	v_mov_b32_e32 v237, v236

; template <int MI, bool SWAP, bool F8 = false>
; __device__ __forceinline__ void gemm_core(const bf16_t* __restrict__ A, int lda, const bf16_t* __restrict__ B, int ldb,
;                                           int K, char* smem, f32x4 (&acc)[MI][4]) {
;     ...
;     for (int kk = 0; kk < 2; ++kk) {
;       const int ch = ((kk * 4 + g) ^ (li & 7)) << 4;
;       bf16x8 xf[MI], wf[4];
; #pragma unroll
;       for (int j = 0; j < 4; ++j) wf[j] = *(const bf16x8*)(smem + wrow + ((j & 1) * 16 + (j >> 1) * 64) * 128 + ch);
; #pragma unroll
;       for (int i = 0; i < MI; ++i) xf[i] = *(const bf16x8*)(smem + xrow + i * 2048 + ch);
; #pragma unroll
;       for (int i = 0; i < MI; ++i)
; #pragma unroll
;         for (int j = 0; j < 4; ++j) {
;           if (SWAP) acc[i][j] = __builtin_amdgcn_mfma_f32_16x16x32_bf16(xf[i], wf[j], acc[i][j], 0, 0, 0);
;           else acc[i][j] = __builtin_amdgcn_mfma_f32_16x16x32_bf16(wf[j], xf[i], acc[i][j], 0, 0, 0);
;         }
;     }
.Lcch819_ret:
	s_add_u32 s63, s63, 1
	s_barrier
	v_add_u32_e32 v213, v202, v204
	ds_read_b128 v[148:151], v215 offset:32768
	ds_read_b128 v[152:155], v215 offset:34816
	ds_read_b128 v[156:159], v213
	ds_read_b128 v[160:163], v213 offset:2048
	ds_read_b128 v[164:167], v215 offset:40960
	ds_read_b128 v[168:171], v215 offset:43008
	s_waitcnt lgkmcnt(3)
	v_mfma_f32_16x16x32_bf16 v[140:143], v[148:151], v[156:159], v[140:143]
	v_add_u32_e32 v207, v203, v205
	v_add_u32_e32 v206, v202, v205
	v_mfma_f32_16x16x32_bf16 v[136:139], v[152:155], v[156:159], v[136:139]
	s_waitcnt lgkmcnt(1)
	v_mfma_f32_16x16x32_bf16 v[132:135], v[164:167], v[156:159], v[132:135]
	s_waitcnt lgkmcnt(0)
	v_mfma_f32_16x16x32_bf16 v[124:127], v[168:171], v[156:159], v[124:127]
	v_mfma_f32_16x16x32_bf16 v[108:111], v[148:151], v[160:163], v[108:111]
	v_mfma_f32_16x16x32_bf16 v[104:107], v[152:155], v[160:163], v[104:107]
	v_mfma_f32_16x16x32_bf16 v[96:99], v[164:167], v[160:163], v[96:99]
	v_mfma_f32_16x16x32_bf16 v[92:95], v[168:171], v[160:163], v[92:95]
	ds_read_b128 v[156:159], v213 offset:4096
	ds_read_b128 v[160:163], v213 offset:6144
	s_waitcnt lgkmcnt(1)
	v_mfma_f32_16x16x32_bf16 v[88:91], v[148:151], v[156:159], v[88:91]
	v_mfma_f32_16x16x32_bf16 v[84:87], v[152:155], v[156:159], v[84:87]
	v_mfma_f32_16x16x32_bf16 v[80:83], v[164:167], v[156:159], v[80:83]
	v_mfma_f32_16x16x32_bf16 v[60:63], v[168:171], v[156:159], v[60:63]
	s_waitcnt lgkmcnt(0)
	v_mfma_f32_16x16x32_bf16 v[56:59], v[148:151], v[160:163], v[56:59]
	v_mfma_f32_16x16x32_bf16 v[52:55], v[152:155], v[160:163], v[52:55]
	v_mfma_f32_16x16x32_bf16 v[48:51], v[164:167], v[160:163], v[48:51]
	v_mfma_f32_16x16x32_bf16 v[44:47], v[168:171], v[160:163], v[44:47]
	ds_read_b128 v[156:159], v213 offset:8192
	ds_read_b128 v[160:163], v213 offset:10240
	s_waitcnt lgkmcnt(1)
	v_mfma_f32_16x16x32_bf16 v[40:43], v[148:151], v[156:159], v[40:43]
	v_mfma_f32_16x16x32_bf16 v[36:39], v[152:155], v[156:159], v[36:39]
	v_mfma_f32_16x16x32_bf16 v[32:35], v[164:167], v[156:159], v[32:35]
	v_mfma_f32_16x16x32_bf16 v[28:31], v[168:171], v[156:159], v[28:31]
	s_waitcnt lgkmcnt(0)
	v_mfma_f32_16x16x32_bf16 v[24:27], v[148:151], v[160:163], v[24:27]
	v_mfma_f32_16x16x32_bf16 v[20:23], v[152:155], v[160:163], v[20:23]
	v_mfma_f32_16x16x32_bf16 v[68:71], v[164:167], v[160:163], v[68:71]
	v_mfma_f32_16x16x32_bf16 v[64:67], v[168:171], v[160:163], v[64:67]
	ds_read_b128 v[156:159], v213 offset:12288
	ds_read_b128 v[160:163], v213 offset:14336
	ds_read_b128 v[172:175], v207 offset:32768
	ds_read_b128 v[180:183], v207 offset:34816
	s_waitcnt lgkmcnt(3)
	v_mfma_f32_16x16x32_bf16 v[72:75], v[148:151], v[156:159], v[72:75]
	v_mfma_f32_16x16x32_bf16 v[76:79], v[152:155], v[156:159], v[76:79]
	v_mfma_f32_16x16x32_bf16 v[128:131], v[164:167], v[156:159], v[128:131]
	v_mfma_f32_16x16x32_bf16 v[120:123], v[168:171], v[156:159], v[120:123]
	s_waitcnt lgkmcnt(2)
	v_mfma_f32_16x16x32_bf16 v[116:119], v[148:151], v[160:163], v[116:119]
	v_mfma_f32_16x16x32_bf16 v[112:115], v[152:155], v[160:163], v[112:115]
	ds_read_b128 v[148:151], v206
	ds_read_b128 v[152:155], v206 offset:2048
	ds_read_b128 v[192:195], v207 offset:40960
	ds_read_b128 v[196:199], v207 offset:43008
	v_mfma_f32_16x16x32_bf16 v[100:103], v[164:167], v[160:163], v[100:103]
	v_mfma_f32_16x16x32_bf16 v[144:147], v[168:171], v[160:163], v[144:147]
	s_waitcnt lgkmcnt(3)
	v_mfma_f32_16x16x32_bf16 v[140:143], v[172:175], v[148:151], v[140:143]
	v_mfma_f32_16x16x32_bf16 v[136:139], v[180:183], v[148:151], v[136:139]
	s_waitcnt lgkmcnt(1)
	v_mfma_f32_16x16x32_bf16 v[132:135], v[192:195], v[148:151], v[132:135]
	s_waitcnt lgkmcnt(0)
	v_mfma_f32_16x16x32_bf16 v[124:127], v[196:199], v[148:151], v[124:127]
	v_mfma_f32_16x16x32_bf16 v[108:111], v[172:175], v[152:155], v[108:111]
	v_mfma_f32_16x16x32_bf16 v[104:107], v[180:183], v[152:155], v[104:107]
	v_mfma_f32_16x16x32_bf16 v[96:99], v[192:195], v[152:155], v[96:99]
	v_mfma_f32_16x16x32_bf16 v[92:95], v[196:199], v[152:155], v[92:95]
	ds_read_b128 v[148:151], v206 offset:4096
	ds_read_b128 v[152:155], v206 offset:6144
	s_waitcnt lgkmcnt(1)
	v_mfma_f32_16x16x32_bf16 v[88:91], v[172:175], v[148:151], v[88:91]
	ds_read_b128 v[156:159], v206 offset:12288
	ds_read_b128 v[216:219], v206 offset:14336
	v_mfma_f32_16x16x32_bf16 v[84:87], v[180:183], v[148:151], v[84:87]
	v_mfma_f32_16x16x32_bf16 v[80:83], v[192:195], v[148:151], v[80:83]
	v_mfma_f32_16x16x32_bf16 v[60:63], v[196:199], v[148:151], v[60:63]
	ds_read_b128 v[148:151], v206 offset:8192
	s_waitcnt lgkmcnt(3)
	v_mfma_f32_16x16x32_bf16 v[56:59], v[172:175], v[152:155], v[56:59]
	v_mfma_f32_16x16x32_bf16 v[52:55], v[180:183], v[152:155], v[52:55]
	v_mfma_f32_16x16x32_bf16 v[48:51], v[192:195], v[152:155], v[48:51]
	v_mfma_f32_16x16x32_bf16 v[44:47], v[196:199], v[152:155], v[44:47]
	ds_read_b128 v[152:155], v206 offset:10240
	s_waitcnt lgkmcnt(1)
	v_mfma_f32_16x16x32_bf16 v[40:43], v[172:175], v[148:151], v[40:43]
	v_mfma_f32_16x16x32_bf16 v[36:39], v[180:183], v[148:151], v[36:39]
	v_mfma_f32_16x16x32_bf16 v[32:35], v[192:195], v[148:151], v[32:35]
	v_mfma_f32_16x16x32_bf16 v[28:31], v[196:199], v[148:151], v[28:31]
	s_waitcnt lgkmcnt(0)
	v_mfma_f32_16x16x32_bf16 v[24:27], v[172:175], v[152:155], v[24:27]
	v_mfma_f32_16x16x32_bf16 v[20:23], v[180:183], v[152:155], v[20:23]
	v_mfma_f32_16x16x32_bf16 v[68:71], v[192:195], v[152:155], v[68:71]
	v_mfma_f32_16x16x32_bf16 v[64:67], v[196:199], v[152:155], v[64:67]
	v_mfma_f32_16x16x32_bf16 v[72:75], v[172:175], v[156:159], v[72:75]
	v_mfma_f32_16x16x32_bf16 v[76:79], v[180:183], v[156:159], v[76:79]
	v_mfma_f32_16x16x32_bf16 v[128:131], v[192:195], v[156:159], v[128:131]
	v_mfma_f32_16x16x32_bf16 v[120:123], v[196:199], v[156:159], v[120:123]
	v_mfma_f32_16x16x32_bf16 v[116:119], v[172:175], v[216:219], v[116:119]
	v_mfma_f32_16x16x32_bf16 v[112:115], v[180:183], v[216:219], v[112:115]
	v_mfma_f32_16x16x32_bf16 v[100:103], v[192:195], v[216:219], v[100:103]
	v_mfma_f32_16x16x32_bf16 v[144:147], v[196:199], v[216:219], v[144:147]
	s_add_u32 s6, s6, 0x80
	s_addc_u32 s7, s7, 0
	s_cmpk_lg_i32 s6, 0x780
	s_cbranch_scc1 .LBB0_819
; template <int MI, bool SWAP, bool F8 = false>
; __device__ __forceinline__ void gemm_core(const bf16_t* __restrict__ A, int lda, const bf16_t* __restrict__ B, int ldb,
;                                           int K, char* smem, f32x4 (&acc)[MI][4]) {
;     ...
;   for (int kt = 0; kt < nk; ++kt) {
;     __syncthreads();
; #pragma unroll
;     for (int i = 0; i < MI; ++i) *(u32x4*)(smem + woff + i * 4096) = ra[i];
; #pragma unroll
;     for (int i = 0; i < 4; ++i) *(u32x4*)(smem + 32768 + woff + i * 4096) = rb[i];
;     __syncthreads();
;     if (kt + 1 < nk) {
; #pragma unroll
;       for (int i = 0; i < MI; ++i) ra[i] = *(const u32x4*)(ap + (size_t)(32 * i) * lda + (kt + 1) * 64);
; #pragma unroll
;       for (int i = 0; i < 4; ++i) rb[i] = *(const u32x4*)(bp + (size_t)(32 * i) * ldb + (kt + 1) * 64);
;     }
;     if (F8) {
;       const int c0 = (g ^ (li & 7)) << 4, c1 = ((4 + g) ^ (li & 7)) << 4;
;       i32x8 wf8[4];
; #pragma unroll
;       for (int j = 0; j < 4; ++j) {
;         const char* rp = smem + wrow + ((j & 1) * 16 + (j >> 1) * 64) * 128;
;         const u32x4 lo = *(const u32x4*)(rp + c0), hi = *(const u32x4*)(rp + c1);
;         wf8[j] = (i32x8){(int)lo.x, (int)lo.y, (int)lo.z, (int)lo.w, (int)hi.x, (int)hi.y, (int)hi.z, (int)hi.w};
;       }
; #pragma unroll
;       for (int i = 0; i < MI; ++i) {
;         const char* rp = smem + xrow + i * 2048;
;         const u32x4 lo = *(const u32x4*)(rp + c0), hi = *(const u32x4*)(rp + c1);
;         const i32x8 xf8 = {(int)lo.x, (int)lo.y, (int)lo.z, (int)lo.w, (int)hi.x, (int)hi.y, (int)hi.z, (int)hi.w};
; #pragma unroll
;         for (int j = 0; j < 4; ++j)
;           acc[i][j] = __builtin_amdgcn_mfma_scale_f32_16x16x128_f8f6f4(wf8[j], xf8, acc[i][j], 0, 0, 0, 0x77777777, 0, 0x7f7f7f7f);
;       }
;     } else {
; #pragma unroll
;     for (int kk = 0; kk < 2; ++kk) {
;       const int ch = ((kk * 4 + g) ^ (li & 7)) << 4;
;       bf16x8 xf[MI], wf[4];
; #pragma unroll
;       for (int j = 0; j < 4; ++j) wf[j] = *(const bf16x8*)(smem + wrow + ((j & 1) * 16 + (j >> 1) * 64) * 128 + ch);
; #pragma unroll
;       for (int i = 0; i < MI; ++i) xf[i] = *(const bf16x8*)(smem + xrow + i * 2048 + ch);
; #pragma unroll
;       for (int i = 0; i < MI; ++i)
; #pragma unroll
;         for (int j = 0; j < 4; ++j) {
	s_barrier
	s_mov_b32 m0, s62
	s_nop 0
	global_load_lds_dwordx4 v252, s[56:57]
	s_add_u32 m0, s62, 0x1000
	s_nop 0
	global_load_lds_dwordx4 v253, s[56:57]
	s_add_u32 s56, s56, 0x20000
	s_addc_u32 s57, s57, 0
	s_add_u32 m0, s62, 0x2000
	s_nop 0
	global_load_lds_dwordx4 v252, s[56:57]
	s_add_u32 m0, s62, 0x3000
	s_nop 0
	global_load_lds_dwordx4 v253, s[56:57]
	s_add_u32 s56, s56, 0x20000
	s_addc_u32 s57, s57, 0
	s_add_u32 m0, s62, 0x4000
	s_nop 0
	global_load_lds_dwordx4 v252, s[56:57]
	s_add_u32 m0, s62, 0x5000
	s_nop 0
	global_load_lds_dwordx4 v253, s[56:57]
	s_add_u32 s56, s56, 0x20000
	s_addc_u32 s57, s57, 0
	s_add_u32 m0, s62, 0x6000
	s_nop 0
	global_load_lds_dwordx4 v252, s[56:57]
	s_add_u32 m0, s62, 0x7000
	s_nop 0
	global_load_lds_dwordx4 v253, s[56:57]
	s_sub_u32 s56, s56, 0x60000
	s_subb_u32 s57, s57, 0
	s_add_u32 m0, s62, 0x8000
	s_nop 0
	global_load_lds_dwordx4 v252, s[58:59]
	s_add_u32 m0, s62, 0x9000
	s_nop 0
	global_load_lds_dwordx4 v253, s[58:59]
	s_add_u32 s58, s58, 0x20000
	s_addc_u32 s59, s59, 0
	s_add_u32 m0, s62, 0xa000
	s_nop 0
	global_load_lds_dwordx4 v252, s[58:59]
	s_add_u32 m0, s62, 0xb000
	s_nop 0
	global_load_lds_dwordx4 v253, s[58:59]
	s_sub_u32 s58, s58, 0x20000
	s_subb_u32 s59, s59, 0
	s_waitcnt vmcnt(0)
	s_barrier
	ds_read_b128 v[148:151], v215 offset:32768
	ds_read_b128 v[152:155], v215 offset:34816
	ds_read_b128 v[156:159], v215 offset:40960
	ds_read_b128 v[160:163], v215 offset:43008
	ds_read_b128 v[164:167], v213
	ds_read_b128 v[168:171], v213 offset:2048
	ds_read_b128 v[172:175], v213 offset:4096
	ds_read_b128 v[176:179], v213 offset:6144
	ds_read_b128 v[180:183], v213 offset:8192
	ds_read_b128 v[184:187], v213 offset:10240
	ds_read_b128 v[188:191], v213 offset:12288
	ds_read_b128 v[192:195], v213 offset:14336
	s_waitcnt lgkmcnt(7)
	v_mfma_f32_16x16x32_bf16 v[132:135], v[156:159], v[164:167], v[132:135]
	s_lshl_b64 s[0:1], s[0:1], 2
	s_add_u32 s0, s16, s0
	s_addc_u32 s1, s17, s1
	v_mfma_f32_16x16x32_bf16 v[140:143], v[148:151], v[164:167], v[140:143]
	s_lshl_b32 s6, s22, 2
	s_add_u32 s0, s0, s6
	s_addc_u32 s1, s1, 0
	v_mfma_f32_16x16x32_bf16 v[136:139], v[152:155], v[164:167], v[136:139]
	s_add_i32 s21, s21, s78
	s_add_i32 s20, s20, s71
	s_add_i32 s19, s19, s76
	v_mfma_f32_16x16x32_bf16 v[124:127], v[160:163], v[164:167], v[124:127]
	s_cmpk_gt_i32 s21, 0x1ff
	s_waitcnt lgkmcnt(6)
	v_mfma_f32_16x16x32_bf16 v[108:111], v[148:151], v[168:171], v[108:111]
	v_mfma_f32_16x16x32_bf16 v[104:107], v[152:155], v[168:171], v[104:107]
	v_mfma_f32_16x16x32_bf16 v[96:99], v[156:159], v[168:171], v[96:99]
	v_mfma_f32_16x16x32_bf16 v[92:95], v[160:163], v[168:171], v[92:95]
	s_waitcnt lgkmcnt(5)
	v_mfma_f32_16x16x32_bf16 v[88:91], v[148:151], v[172:175], v[88:91]
	v_mfma_f32_16x16x32_bf16 v[84:87], v[152:155], v[172:175], v[84:87]
	v_mfma_f32_16x16x32_bf16 v[80:83], v[156:159], v[172:175], v[80:83]
	v_mfma_f32_16x16x32_bf16 v[60:63], v[160:163], v[172:175], v[60:63]
	s_waitcnt lgkmcnt(4)
	v_mfma_f32_16x16x32_bf16 v[56:59], v[148:151], v[176:179], v[56:59]
	v_mfma_f32_16x16x32_bf16 v[52:55], v[152:155], v[176:179], v[52:55]
	v_mfma_f32_16x16x32_bf16 v[48:51], v[156:159], v[176:179], v[48:51]
	v_mfma_f32_16x16x32_bf16 v[44:47], v[160:163], v[176:179], v[44:47]
	s_waitcnt lgkmcnt(3)
	v_mfma_f32_16x16x32_bf16 v[40:43], v[148:151], v[180:183], v[40:43]
	v_mfma_f32_16x16x32_bf16 v[36:39], v[152:155], v[180:183], v[36:39]
	v_mfma_f32_16x16x32_bf16 v[32:35], v[156:159], v[180:183], v[32:35]
	v_mfma_f32_16x16x32_bf16 v[28:31], v[160:163], v[180:183], v[28:31]
	s_waitcnt lgkmcnt(2)
	v_mfma_f32_16x16x32_bf16 v[24:27], v[148:151], v[184:187], v[24:27]
	v_mfma_f32_16x16x32_bf16 v[20:23], v[152:155], v[184:187], v[20:23]
	v_mfma_f32_16x16x32_bf16 v[164:167], v[156:159], v[184:187], v[68:71]
	v_mfma_f32_16x16x32_bf16 v[168:171], v[160:163], v[184:187], v[64:67]
	s_waitcnt lgkmcnt(1)
	v_mfma_f32_16x16x32_bf16 v[172:175], v[148:151], v[188:191], v[72:75]
	v_mfma_f32_16x16x32_bf16 v[176:179], v[152:155], v[188:191], v[76:79]
	v_mfma_f32_16x16x32_bf16 v[180:183], v[156:159], v[188:191], v[128:131]
	v_mfma_f32_16x16x32_bf16 v[184:187], v[160:163], v[188:191], v[120:123]
	s_waitcnt lgkmcnt(0)
	v_mfma_f32_16x16x32_bf16 v[148:151], v[148:151], v[192:195], v[116:119]
	v_mfma_f32_16x16x32_bf16 v[152:155], v[152:155], v[192:195], v[112:115]
	v_mfma_f32_16x16x32_bf16 v[156:159], v[156:159], v[192:195], v[100:103]
	v_mfma_f32_16x16x32_bf16 v[144:147], v[160:163], v[192:195], v[144:147]
	ds_read_b128 v[160:163], v207 offset:32768
	ds_read_b128 v[188:191], v207 offset:34816
	ds_read_b128 v[192:195], v207 offset:40960
	ds_read_b128 v[196:199], v207 offset:43008
	ds_read_b128 v[64:67], v206
	ds_read_b128 v[68:71], v206 offset:2048
	ds_read_b128 v[72:75], v206 offset:4096
	ds_read_b128 v[76:79], v206 offset:6144
	ds_read_b128 v[200:203], v206 offset:8192
	ds_read_b128 v[216:219], v206 offset:10240
	ds_read_b128 v[220:223], v206 offset:12288
	ds_read_b128 v[204:207], v206 offset:14336
	s_waitcnt lgkmcnt(7)
; template <bool ACCUM, int MI>
; __device__ void gemm_tile_f32(const bf16_t* A, int lda, const bf16_t* B, int ldb, int K, float* C, int ldc, char* smem) {
;     ...
; #pragma unroll
;   for (int i = 0; i < MI; ++i)
; #pragma unroll
;     for (int j = 0; j < 4; ++j) {
;       f32x4* cp = (f32x4*)(C + (size_t)MROW(i) * ldc + NCOL(j));
;       f32x4 v = acc[i][j];
;       if (ACCUM) v += *cp;
;       *cp = v;
;     }
	v_mfma_f32_16x16x32_bf16 v[224:227], v[192:195], v[64:67], v[132:135]
	v_mfma_f32_16x16x32_bf16 v[228:231], v[196:199], v[64:67], v[124:127]
	s_waitcnt lgkmcnt(6)
	v_mfma_f32_16x16x32_bf16 v[128:131], v[160:163], v[68:71], v[108:111]
	v_mfma_f32_16x16x32_bf16 v[124:127], v[188:191], v[68:71], v[104:107]
	s_waitcnt lgkmcnt(5)
	v_mfma_f32_16x16x32_bf16 v[112:115], v[160:163], v[72:75], v[88:91]
	v_mfma_f32_16x16x32_bf16 v[108:111], v[188:191], v[72:75], v[84:87]
	v_mfma_f32_16x16x32_bf16 v[104:107], v[192:195], v[72:75], v[80:83]
	v_mfma_f32_16x16x32_bf16 v[100:103], v[196:199], v[72:75], v[60:63]
	s_waitcnt lgkmcnt(3)
	v_mfma_f32_16x16x32_bf16 v[72:75], v[192:195], v[200:203], v[32:35]
	s_waitcnt lgkmcnt(0)
	v_mfma_f32_16x16x32_bf16 v[32:35], v[160:163], v[204:207], v[148:151]
	v_mfma_f32_16x16x32_bf16 v[60:63], v[188:191], v[216:219], v[20:23]
	v_mfma_f32_16x16x32_bf16 v[20:23], v[196:199], v[204:207], v[144:147]
	v_mfma_f32_16x16x32_bf16 v[140:143], v[160:163], v[64:67], v[140:143]
	v_mfma_f32_16x16x32_bf16 v[136:139], v[188:191], v[64:67], v[136:139]
	v_mfma_f32_16x16x32_bf16 v[120:123], v[192:195], v[68:71], v[96:99]
	v_mfma_f32_16x16x32_bf16 v[116:119], v[196:199], v[68:71], v[92:95]
	v_mfma_f32_16x16x32_bf16 v[96:99], v[160:163], v[76:79], v[56:59]
	v_mfma_f32_16x16x32_bf16 v[92:95], v[188:191], v[76:79], v[52:55]
	v_mfma_f32_16x16x32_bf16 v[88:91], v[192:195], v[76:79], v[48:51]
	v_mfma_f32_16x16x32_bf16 v[84:87], v[196:199], v[76:79], v[44:47]
	v_mfma_f32_16x16x32_bf16 v[80:83], v[160:163], v[200:203], v[40:43]
	v_mfma_f32_16x16x32_bf16 v[76:79], v[188:191], v[200:203], v[36:39]
	v_mfma_f32_16x16x32_bf16 v[68:71], v[196:199], v[200:203], v[28:31]
	v_mfma_f32_16x16x32_bf16 v[64:67], v[160:163], v[216:219], v[24:27]
	v_mfma_f32_16x16x32_bf16 v[56:59], v[192:195], v[216:219], v[164:167]
	v_mfma_f32_16x16x32_bf16 v[52:55], v[196:199], v[216:219], v[168:171]
	v_mfma_f32_16x16x32_bf16 v[48:51], v[160:163], v[220:223], v[172:175]
	v_mfma_f32_16x16x32_bf16 v[44:47], v[188:191], v[220:223], v[176:179]
	v_mfma_f32_16x16x32_bf16 v[40:43], v[192:195], v[220:223], v[180:183]
	v_mfma_f32_16x16x32_bf16 v[36:39], v[196:199], v[220:223], v[184:187]
	v_mfma_f32_16x16x32_bf16 v[28:31], v[188:191], v[204:207], v[152:155]
	v_mfma_f32_16x16x32_bf16 v[24:27], v[192:195], v[204:207], v[156:159]
	s_nop 7
	s_nop 7
	s_nop 7
	global_store_dwordx4 v237, v[140:143], s[98:99]
	global_store_dwordx4 v237, v[136:139], s[98:99] offset:64
	global_store_dwordx4 v237, v[224:227], s[98:99] offset:256
	global_store_dwordx4 v237, v[228:231], s[98:99] offset:320
	v_add_u32_e32 v237, 0x10000, v237
	global_store_dwordx4 v237, v[128:131], s[98:99]
	global_store_dwordx4 v237, v[124:127], s[98:99] offset:64
	global_store_dwordx4 v237, v[120:123], s[98:99] offset:256
	global_store_dwordx4 v237, v[116:119], s[98:99] offset:320
	v_add_u32_e32 v237, 0x10000, v237
	global_store_dwordx4 v237, v[112:115], s[98:99]
	global_store_dwordx4 v237, v[108:111], s[98:99] offset:64
	global_store_dwordx4 v237, v[104:107], s[98:99] offset:256
	global_store_dwordx4 v237, v[100:103], s[98:99] offset:320
	v_add_u32_e32 v237, 0x10000, v237
	global_store_dwordx4 v237, v[96:99], s[98:99]
	global_store_dwordx4 v237, v[92:95], s[98:99] offset:64
	global_store_dwordx4 v237, v[88:91], s[98:99] offset:256
	global_store_dwordx4 v237, v[84:87], s[98:99] offset:320
	v_add_u32_e32 v237, 0x10000, v237
	global_store_dwordx4 v237, v[80:83], s[98:99]
	global_store_dwordx4 v237, v[76:79], s[98:99] offset:64
	global_store_dwordx4 v237, v[72:75], s[98:99] offset:256
	global_store_dwordx4 v237, v[68:71], s[98:99] offset:320
	v_add_u32_e32 v237, 0x10000, v237
	global_store_dwordx4 v237, v[64:67], s[98:99]
	global_store_dwordx4 v237, v[60:63], s[98:99] offset:64
	global_store_dwordx4 v237, v[56:59], s[98:99] offset:256
	global_store_dwordx4 v237, v[52:55], s[98:99] offset:320
	v_add_u32_e32 v237, 0x10000, v237
	global_store_dwordx4 v237, v[48:51], s[98:99]
	global_store_dwordx4 v237, v[44:47], s[98:99] offset:64
	global_store_dwordx4 v237, v[40:43], s[98:99] offset:256
	global_store_dwordx4 v237, v[36:39], s[98:99] offset:320
	v_add_u32_e32 v237, 0x10000, v237
	global_store_dwordx4 v237, v[32:35], s[98:99]
	global_store_dwordx4 v237, v[28:31], s[98:99] offset:64
	global_store_dwordx4 v237, v[24:27], s[98:99] offset:256
	global_store_dwordx4 v237, v[20:23], s[98:99] offset:320
	s_cbranch_scc0 .LBB0_818
